# also .p2align 6 on the scores and P.V unit-loop heads (all five GEMM loop heads 64-byte aligned)
# baseline (speedup 1.0000x reference)
; #define GP_STAGE(bufoff, gbase, voff) do { _Pragma("unroll") for (int _i = 0; _i < 2; ++_i) \
;         __builtin_amdgcn_global_load_lds((const unsigned*)((const char*)(gbase) + (voff)[_i]), (LAS unsigned*)(lds + (bufoff) + ldsw + _i * 8192), 16, 0, 0); } while (0)
; #define GP_LDA(dst, b, h) do { _Pragma("unroll") for (int m = 0; m < 4; ++m) _Pragma("unroll") for (int k = 0; k < 2; ++k) dst[m][k] = *(const LAS bf16x8*)(lds + GP_SA(b, h) + aoff + m * 2048 + k * 1024); } while (0)
; #define GP_LDB(dst, b, h) do { _Pragma("unroll") for (int n = 0; n < 2; ++n) _Pragma("unroll") for (int k = 0; k < 2; ++k) dst[n][k] = *(const LAS bf16x8*)(lds + GP_SB(b, h) + boff + n * 2048 + k * 1024); } while (0)
; #define GP_SCHED __builtin_amdgcn_sched_barrier(0)
; template <class Epi, class Sched>
; __device__ __forceinline__ void gemm_phase(LAS unsigned char* lds, const int lda, const int ldb, const int K, const Sched& S, const Epi& E, const int widx) {
;     ...
;     for (;;) {
;         const bool has_next = S.next(ui + 1, nxt);
;         const char* nA = has_next ? nxt.A : cA; const char* nB = has_next ? nxt.B : cB;
;         for (int t = 0; t < nt; t += 2) {
;             const bool last = (t == nt - 2);
;             const char* a1 = cA + (size_t)(t + 1) * kstep;
;             const char* a2 = last ? nA : cA + (size_t)(t + 2) * kstep; const char* b2 = last ? nB : cB + (size_t)(t + 2) * kstep;
;             const char* a3 = a2 + kstep; const char* b3 = b2 + kstep;
;             GP_LDB(B0, 0, 0); GP_LDB(B1, 0, 1); GP_SCHED; GP_LDA(At, 0, 0); GP_STAGE(GP_SA(1, 1), a1 + hstepA, voffA);
;     __device__ __forceinline__ bool next(int i, Unit& u) const {
;         const int L = i * G + c; if (L >= 512) return false;
.LBB0_359:
	s_add_i32 s41, s41, s3
	s_mov_b64 s[28:29], 0
	.p2align	6

; #define GP_STAGE(bufoff, gbase, voff) do { _Pragma("unroll") for (int _i = 0; _i < 2; ++_i) \
;         __builtin_amdgcn_global_load_lds((const unsigned*)((const char*)(gbase) + (voff)[_i]), (LAS unsigned*)(lds + (bufoff) + ldsw + _i * 8192), 16, 0, 0); } while (0)
; #define GP_LDA(dst, b, h) do { _Pragma("unroll") for (int m = 0; m < 4; ++m) _Pragma("unroll") for (int k = 0; k < 2; ++k) dst[m][k] = *(const LAS bf16x8*)(lds + GP_SA(b, h) + aoff + m * 2048 + k * 1024); } while (0)
; #define GP_LDB(dst, b, h) do { _Pragma("unroll") for (int n = 0; n < 2; ++n) _Pragma("unroll") for (int k = 0; k < 2; ++k) dst[n][k] = *(const LAS bf16x8*)(lds + GP_SB(b, h) + boff + n * 2048 + k * 1024); } while (0)
; #define GP_SCHED __builtin_amdgcn_sched_barrier(0)
; template <class Epi, class Sched>
; __device__ __forceinline__ void gemm_phase(LAS unsigned char* lds, const int lda, const int ldb, const int K, const Sched& S, const Epi& E, const int widx) {
;     ...
;     for (;;) {
;         const bool has_next = S.next(ui + 1, nxt);
;         const char* nA = has_next ? nxt.A : cA; const char* nB = has_next ? nxt.B : cB;
;         for (int t = 0; t < nt; t += 2) {
;             const bool last = (t == nt - 2);
;             const char* a1 = cA + (size_t)(t + 1) * kstep;
;             const char* a2 = last ? nA : cA + (size_t)(t + 2) * kstep; const char* b2 = last ? nB : cB + (size_t)(t + 2) * kstep;
;             const char* a3 = a2 + kstep; const char* b3 = b2 + kstep;
;             GP_LDB(B0, 0, 0); GP_LDB(B1, 0, 1); GP_SCHED; GP_LDA(At, 0, 0); GP_STAGE(GP_SA(1, 1), a1 + hstepA, voffA);
;     __device__ __forceinline__ bool next(int i, Unit& u) const {
;         const int L = i * G + c; if (L >= 512) return false;
.LBB0_462:
	s_add_i32 s64, s64, s3
	s_mov_b64 s[28:29], 0
	.p2align	6
